# MLA rescale blocks moved out of line so the no-rescale path falls through (code layout)
# baseline (speedup 1.0000x reference)
.LBB0_546:
	s_or_b64 exec, exec, s[24:25]
	global_load_dwordx4 v[206:209], v[252:253], off
	s_mov_b64 s[0:1], 0x10000
	v_lshl_add_u64 v[250:251], v[250:251], 0, s[0:1]
	v_lshl_add_u64 v[252:253], v[252:253], 0, s[0:1]
	v_exp_f32_e32 v0, v82
	v_exp_f32_e32 v34, v83
	v_mfma_f32_32x32x16_bf16 v[114:129], v[98:101], v[150:153], v[66:81]
	v_exp_f32_e32 v36, v85
	v_add_f32_e32 v35, v34, v0
	v_cvt_pk_bf16_f32 v34, v0, v34
	v_exp_f32_e32 v0, v84
	s_nop 0
	v_add_f32_e32 v35, v0, v35
	v_add_f32_e32 v37, v36, v35
	v_cvt_pk_bf16_f32 v35, v0, v36
	v_exp_f32_e32 v0, v86
	v_mfma_f32_32x32x16_bf16 v[98:113], v[202:205], v[150:153], v[66:81]
	v_exp_f32_e32 v36, v87
	v_exp_f32_e32 v38, v88
	v_exp_f32_e32 v39, v89
	v_add_f32_e32 v37, v0, v37
	v_add_f32_e32 v37, v36, v37
	v_cvt_pk_bf16_f32 v36, v0, v36
	v_add_f32_e32 v0, v38, v37
	v_add_f32_e32 v0, v39, v0
	v_cvt_pk_bf16_f32 v37, v38, v39
	v_exp_f32_e32 v38, v90
	v_exp_f32_e32 v39, v91
	v_mfma_f32_32x32x16_bf16 v[114:129], v[198:201], v[146:149], v[114:129]
	v_exp_f32_e32 v40, v93
	v_add_f32_e32 v0, v38, v0
	v_add_f32_e32 v0, v39, v0
	v_cvt_pk_bf16_f32 v38, v38, v39
	v_exp_f32_e32 v39, v92
	s_nop 0
	v_add_f32_e32 v0, v39, v0
	v_add_f32_e32 v0, v40, v0
	v_cvt_pk_bf16_f32 v39, v39, v40
	v_exp_f32_e32 v40, v94
	v_exp_f32_e32 v41, v95
	v_mfma_f32_32x32x16_bf16 v[98:113], v[194:197], v[146:149], v[98:113]
	v_exp_f32_e32 v42, v97
	v_add_f32_e32 v0, v40, v0
	v_add_f32_e32 v0, v41, v0
	v_cvt_pk_bf16_f32 v40, v40, v41
	v_exp_f32_e32 v41, v96
	s_nop 0
	v_add_f32_e32 v0, v41, v0
	v_add_f32_e32 v0, v42, v0
	v_cvt_pk_bf16_f32 v41, v41, v42
	v_mfma_f32_32x32x16_bf16 v[114:129], v[190:193], v[142:145], v[114:129]
	s_waitcnt lgkmcnt(0)
	s_barrier
	ds_read_b64_tr_b16 v[82:83], v231 offset:26624
	ds_read_b64_tr_b16 v[84:85], v231 offset:27392
	ds_read_b64_tr_b16 v[46:47], v231 offset:26688
	ds_read_b64_tr_b16 v[48:49], v231 offset:27456
	v_exp_f32_e32 v42, v50
	v_exp_f32_e32 v43, v51
	v_add_f32_e32 v0, v42, v0
	v_add_f32_e32 v0, v43, v0
	v_cvt_pk_bf16_f32 v42, v42, v43
	v_mfma_f32_32x32x16_bf16 v[98:113], v[186:189], v[142:145], v[98:113]
	v_exp_f32_e32 v43, v52
	v_exp_f32_e32 v44, v53
	ds_read_b64_tr_b16 v[86:87], v231 offset:29696
	ds_read_b64_tr_b16 v[88:89], v231 offset:30464
	v_add_f32_e32 v0, v43, v0
	v_add_f32_e32 v0, v44, v0
	v_cvt_pk_bf16_f32 v43, v43, v44
	v_mfma_f32_32x32x16_bf16 v[114:129], v[182:185], v[138:141], v[114:129]
	v_exp_f32_e32 v44, v54
	v_exp_f32_e32 v45, v55
	ds_read_b64_tr_b16 v[90:91], v231 offset:29760
	ds_read_b64_tr_b16 v[92:93], v231 offset:30528
	v_add_f32_e32 v0, v44, v0
	v_add_f32_e32 v0, v45, v0
	v_cvt_pk_bf16_f32 v44, v44, v45
	v_mfma_f32_32x32x16_bf16 v[98:113], v[178:181], v[138:141], v[98:113]
	v_exp_f32_e32 v45, v56
	v_exp_f32_e32 v50, v57
	ds_read_b64_tr_b16 v[94:95], v231 offset:32768
	ds_read_b64_tr_b16 v[96:97], v231 offset:33536
	v_add_f32_e32 v0, v45, v0
	v_add_f32_e32 v0, v50, v0
	v_cvt_pk_bf16_f32 v45, v45, v50
	v_mfma_f32_32x32x16_bf16 v[114:129], v[174:177], v[134:137], v[114:129]
	v_exp_f32_e32 v50, v58
	v_exp_f32_e32 v51, v59
	ds_read_b64_tr_b16 v[210:211], v231 offset:32832
	ds_read_b64_tr_b16 v[212:213], v231 offset:33600
	v_add_f32_e32 v0, v50, v0
	v_add_f32_e32 v0, v51, v0
	v_cvt_pk_bf16_f32 v54, v50, v51
	v_mfma_f32_32x32x16_bf16 v[98:113], v[170:173], v[134:137], v[98:113]
	v_exp_f32_e32 v50, v60
	v_exp_f32_e32 v51, v61
	ds_read_b64_tr_b16 v[58:59], v231 offset:35840
	ds_read_b64_tr_b16 v[60:61], v231 offset:36608
	v_add_f32_e32 v0, v50, v0
	v_add_f32_e32 v0, v51, v0
	v_cvt_pk_bf16_f32 v55, v50, v51
	v_mfma_f32_32x32x16_bf16 v[114:129], v[166:169], v[130:133], v[114:129]
	v_exp_f32_e32 v50, v62
	v_exp_f32_e32 v51, v63
	ds_read_b64_tr_b16 v[214:215], v231 offset:35904
	ds_read_b64_tr_b16 v[216:217], v231 offset:36672
	v_add_f32_e32 v0, v50, v0
	v_add_f32_e32 v0, v51, v0
	v_cvt_pk_bf16_f32 v56, v50, v51
	v_mfma_f32_32x32x16_bf16 v[98:113], v[158:161], v[130:133], v[98:113]
	v_exp_f32_e32 v50, v64
	v_exp_f32_e32 v51, v65
	v_add_f32_e32 v0, v50, v0
	v_add_f32_e32 v62, v51, v0
	v_cvt_pk_bf16_f32 v57, v50, v51
	s_waitcnt lgkmcnt(14)
	v_mfma_f32_32x32x16_bf16 v[18:33], v[82:85], v[34:37], v[18:33]
	ds_read_b128 v[50:53], v233
	ds_read_b128 v[198:201], v233 offset:6656
	v_add_f32_e32 v0, v242, v62
	s_waitcnt lgkmcnt(14)
	v_mfma_f32_32x32x16_bf16 v[2:17], v[46:49], v[34:37], v[2:17]
	ds_read_b128 v[202:205], v233 offset:32
	ds_read_b128 v[194:197], v233 offset:6688
	s_waitcnt lgkmcnt(14)
	v_mfma_f32_32x32x16_bf16 v[18:33], v[86:89], v[38:41], v[18:33]
	ds_read_b128 v[190:193], v233 offset:64
	ds_read_b128 v[186:189], v233 offset:6720
	s_waitcnt lgkmcnt(14)
	v_mfma_f32_32x32x16_bf16 v[2:17], v[90:93], v[38:41], v[2:17]
	ds_read_b128 v[182:185], v233 offset:96
	ds_read_b128 v[178:181], v233 offset:6752
	s_waitcnt lgkmcnt(14)
	v_mfma_f32_32x32x16_bf16 v[18:33], v[94:97], v[42:45], v[18:33]
	ds_read_b128 v[174:177], v233 offset:128
	ds_read_b128 v[170:173], v233 offset:6784
	s_waitcnt lgkmcnt(14)
	v_mfma_f32_32x32x16_bf16 v[2:17], v[210:213], v[42:45], v[2:17]
	ds_read_b128 v[166:169], v233 offset:160
	ds_read_b128 v[158:161], v233 offset:6816
	s_waitcnt lgkmcnt(14)
	v_mfma_f32_32x32x16_bf16 v[18:33], v[58:61], v[54:57], v[18:33]
	s_waitcnt lgkmcnt(12)
	v_mfma_f32_32x32x16_bf16 v[2:17], v[214:217], v[54:57], v[2:17]
	v_mov_b32_e32 v34, v62
	s_nop 1
	v_permlane32_swap_b32_e32 v62, v34
	v_max_f32_e32 v34, v62, v34
	v_cmp_lt_f32_e32 vcc, s74, v34
	s_cbranch_vccnz .Lmla_rs1
.Lmla_j1:
	s_waitcnt vmcnt(1)
	ds_write_b128 v232, v[162:165] offset:13312
	s_and_saveexec_b64 s[24:25], s[4:5]
.LBB0_548:
	v_add_u32_e32 v54, v241, v220
	ds_write_b128 v54, v[154:157] offset:13440

.LBB0_553:
	global_load_dwordx4 v[206:209], v[252:253], off
	s_mov_b64 s[0:1], 0x10000
	v_lshl_add_u64 v[250:251], v[250:251], 0, s[0:1]
	v_lshl_add_u64 v[252:253], v[252:253], 0, s[0:1]
	v_mfma_f32_32x32x16_bf16 v[82:97], v[50:53], v[150:153], v[66:81]
	v_exp_f32_e32 v50, v114
	v_exp_f32_e32 v51, v115
	v_add_f32_e32 v52, 0, v50
	v_cvt_pk_bf16_f32 v114, v50, v51
	v_exp_f32_e32 v50, v116
	v_add_f32_e32 v52, v51, v52
	v_exp_f32_e32 v51, v117
	v_add_f32_e32 v52, v50, v52
	v_add_f32_e32 v52, v51, v52
	v_cvt_pk_bf16_f32 v115, v50, v51
	v_exp_f32_e32 v116, v118
	v_exp_f32_e32 v117, v119
	v_exp_f32_e32 v118, v120
	v_exp_f32_e32 v119, v121
	v_add_f32_e32 v50, v116, v52
	v_add_f32_e32 v120, v117, v50
	v_mfma_f32_32x32x16_bf16 v[50:65], v[198:201], v[150:153], v[66:81]
	v_cvt_pk_bf16_f32 v116, v116, v117
	v_add_f32_e32 v117, v118, v120
	v_add_f32_e32 v120, v119, v117
	v_cvt_pk_bf16_f32 v117, v118, v119
	v_exp_f32_e32 v118, v122
	v_exp_f32_e32 v119, v123
	v_mfma_f32_32x32x16_bf16 v[82:97], v[202:205], v[146:149], v[82:97]
	v_exp_f32_e32 v121, v125
	v_add_f32_e32 v120, v118, v120
	v_add_f32_e32 v120, v119, v120
	v_cvt_pk_bf16_f32 v118, v118, v119
	v_exp_f32_e32 v119, v124
	s_nop 0
	v_add_f32_e32 v120, v119, v120
	v_add_f32_e32 v120, v121, v120
	v_cvt_pk_bf16_f32 v119, v119, v121
	v_exp_f32_e32 v121, v126
	v_exp_f32_e32 v122, v127
	v_mfma_f32_32x32x16_bf16 v[50:65], v[194:197], v[146:149], v[50:65]
	v_add_f32_e32 v120, v121, v120
	v_add_f32_e32 v123, v122, v120
	v_cvt_pk_bf16_f32 v120, v121, v122
	v_exp_f32_e32 v121, v128
	v_exp_f32_e32 v122, v129
	v_add_f32_e32 v123, v121, v123
	v_add_f32_e32 v123, v122, v123
	v_cvt_pk_bf16_f32 v121, v121, v122
	v_mfma_f32_32x32x16_bf16 v[82:97], v[190:193], v[142:145], v[82:97]
	s_waitcnt lgkmcnt(0)
	s_barrier
	ds_read_b64_tr_b16 v[190:191], v231 offset:38912
	ds_read_b64_tr_b16 v[192:193], v231 offset:39680
	ds_read_b64_tr_b16 v[126:127], v231 offset:38976
	ds_read_b64_tr_b16 v[128:129], v231 offset:39744
	v_exp_f32_e32 v98, v98
	v_exp_f32_e32 v99, v99
	v_add_f32_e32 v122, v98, v123
	v_add_f32_e32 v123, v99, v122
	v_cvt_pk_bf16_f32 v122, v98, v99
	v_mfma_f32_32x32x16_bf16 v[50:65], v[186:189], v[142:145], v[50:65]
	v_exp_f32_e32 v98, v100
	v_exp_f32_e32 v99, v101
	ds_read_b64_tr_b16 v[186:187], v231 offset:41984
	ds_read_b64_tr_b16 v[188:189], v231 offset:42752
	v_add_f32_e32 v100, v98, v123
	v_add_f32_e32 v100, v99, v100
	v_cvt_pk_bf16_f32 v123, v98, v99
	v_mfma_f32_32x32x16_bf16 v[82:97], v[182:185], v[138:141], v[82:97]
	v_exp_f32_e32 v98, v102
	v_exp_f32_e32 v99, v103
	ds_read_b64_tr_b16 v[182:183], v231 offset:42048
	ds_read_b64_tr_b16 v[184:185], v231 offset:42816
	v_add_f32_e32 v100, v98, v100
	v_add_f32_e32 v100, v99, v100
	v_cvt_pk_bf16_f32 v124, v98, v99
	v_mfma_f32_32x32x16_bf16 v[50:65], v[178:181], v[138:141], v[50:65]
	v_exp_f32_e32 v98, v104
	v_exp_f32_e32 v99, v105
	ds_read_b64_tr_b16 v[210:211], v231 offset:45056
	ds_read_b64_tr_b16 v[212:213], v231 offset:45824
	v_add_f32_e32 v100, v98, v100
	v_add_f32_e32 v100, v99, v100
	v_cvt_pk_bf16_f32 v125, v98, v99
	v_mfma_f32_32x32x16_bf16 v[82:97], v[174:177], v[134:137], v[82:97]
	v_exp_f32_e32 v98, v106
	v_exp_f32_e32 v99, v107
	ds_read_b64_tr_b16 v[214:215], v231 offset:45120
	ds_read_b64_tr_b16 v[216:217], v231 offset:45888
	v_add_f32_e32 v100, v98, v100
	v_add_f32_e32 v100, v99, v100
	v_cvt_pk_bf16_f32 v102, v98, v99
	v_mfma_f32_32x32x16_bf16 v[50:65], v[170:173], v[134:137], v[50:65]
	v_exp_f32_e32 v98, v108
	v_exp_f32_e32 v99, v109
	ds_read_b64_tr_b16 v[106:107], v231 offset:48128
	ds_read_b64_tr_b16 v[108:109], v231 offset:48896
	v_add_f32_e32 v100, v98, v100
	v_add_f32_e32 v100, v99, v100
	v_cvt_pk_bf16_f32 v103, v98, v99
	v_mfma_f32_32x32x16_bf16 v[82:97], v[166:169], v[130:133], v[82:97]
	v_exp_f32_e32 v98, v110
	v_exp_f32_e32 v99, v111
	ds_read_b64_tr_b16 v[244:245], v231 offset:48192
	ds_read_b64_tr_b16 v[246:247], v231 offset:48960
	v_add_f32_e32 v100, v98, v100
	v_add_f32_e32 v100, v99, v100
	v_cvt_pk_bf16_f32 v104, v98, v99
	v_mfma_f32_32x32x16_bf16 v[50:65], v[158:161], v[130:133], v[50:65]
	v_exp_f32_e32 v98, v112
	v_exp_f32_e32 v99, v113
	v_add_f32_e32 v100, v98, v100
	v_add_f32_e32 v110, v99, v100
	v_cvt_pk_bf16_f32 v105, v98, v99
	s_waitcnt lgkmcnt(14)
	v_mfma_f32_32x32x16_bf16 v[18:33], v[190:193], v[114:117], v[18:33]
	ds_read_b128 v[98:101], v233 offset:13312
	ds_read_b128 v[202:205], v233 offset:19968
	v_add_f32_e32 v242, v0, v110
	s_waitcnt lgkmcnt(14)
	v_mfma_f32_32x32x16_bf16 v[2:17], v[126:129], v[114:117], v[2:17]
	ds_read_b128 v[198:201], v233 offset:13344
	ds_read_b128 v[194:197], v233 offset:20000
	s_waitcnt lgkmcnt(14)
	v_mfma_f32_32x32x16_bf16 v[18:33], v[186:189], v[118:121], v[18:33]
	ds_read_b128 v[190:193], v233 offset:13376
	ds_read_b128 v[186:189], v233 offset:20032
	s_waitcnt lgkmcnt(14)
	v_mfma_f32_32x32x16_bf16 v[2:17], v[182:185], v[118:121], v[2:17]
	ds_read_b128 v[182:185], v233 offset:13408
	ds_read_b128 v[178:181], v233 offset:20064
	s_waitcnt lgkmcnt(14)
	v_mfma_f32_32x32x16_bf16 v[18:33], v[210:213], v[122:125], v[18:33]
	ds_read_b128 v[174:177], v233 offset:13440
	ds_read_b128 v[170:173], v233 offset:20096
	s_waitcnt lgkmcnt(14)
	v_mfma_f32_32x32x16_bf16 v[2:17], v[214:217], v[122:125], v[2:17]
	ds_read_b128 v[166:169], v233 offset:13472
	ds_read_b128 v[158:161], v233 offset:20128
	s_waitcnt lgkmcnt(14)
	v_mfma_f32_32x32x16_bf16 v[18:33], v[106:109], v[102:105], v[18:33]
	s_waitcnt lgkmcnt(12)
	v_mfma_f32_32x32x16_bf16 v[2:17], v[244:247], v[102:105], v[2:17]
	v_mov_b32_e32 v0, v110
	s_nop 1
	v_permlane32_swap_b32_e32 v110, v0
	v_max_f32_e32 v0, v110, v0
	v_cmp_lt_f32_e32 vcc, s74, v0
	s_cbranch_vccnz .Lmla_rs2

.Lmla_rs2:
	v_frexp_exp_i32_f32_e32 v0, v0
	v_cvt_f32_i32_e32 v0, v0
	v_cndmask_b32_e32 v35, 0, v0, vcc
	v_exp_f32_e64 v0, -v35
	v_add_f32_e32 v235, v235, v35
	v_xor_b32_e32 v34, 0x80000000, v235
	v_sub_f32_e32 v97, v97, v35
	v_pk_mul_f32 v[32:33], v[32:33], v[0:1] op_sel_hi:[1,0]
	v_pk_mul_f32 v[30:31], v[30:31], v[0:1] op_sel_hi:[1,0]
	v_pk_mul_f32 v[28:29], v[28:29], v[0:1] op_sel_hi:[1,0]
	v_pk_mul_f32 v[26:27], v[26:27], v[0:1] op_sel_hi:[1,0]
	v_pk_mul_f32 v[24:25], v[24:25], v[0:1] op_sel_hi:[1,0]
	v_pk_mul_f32 v[22:23], v[22:23], v[0:1] op_sel_hi:[1,0]
	v_pk_mul_f32 v[20:21], v[20:21], v[0:1] op_sel_hi:[1,0]
	v_pk_mul_f32 v[18:19], v[18:19], v[0:1] op_sel_hi:[1,0]
	v_pk_mul_f32 v[16:17], v[16:17], v[0:1] op_sel_hi:[1,0]
	v_pk_mul_f32 v[14:15], v[14:15], v[0:1] op_sel_hi:[1,0]
	v_pk_mul_f32 v[12:13], v[12:13], v[0:1] op_sel_hi:[1,0]
	v_pk_mul_f32 v[10:11], v[10:11], v[0:1] op_sel_hi:[1,0]
	v_pk_mul_f32 v[8:9], v[8:9], v[0:1] op_sel_hi:[1,0]
	v_pk_mul_f32 v[6:7], v[6:7], v[0:1] op_sel_hi:[1,0]
	v_pk_mul_f32 v[4:5], v[4:5], v[0:1] op_sel_hi:[1,0]
	v_pk_mul_f32 v[2:3], v[2:3], v[0:1] op_sel_hi:[1,0]
	v_sub_f32_e32 v96, v96, v35
	v_sub_f32_e32 v95, v95, v35
	v_sub_f32_e32 v94, v94, v35
	v_sub_f32_e32 v93, v93, v35
	v_sub_f32_e32 v92, v92, v35
	v_sub_f32_e32 v91, v91, v35
	v_sub_f32_e32 v90, v90, v35
	v_sub_f32_e32 v89, v89, v35
	v_sub_f32_e32 v88, v88, v35
	v_sub_f32_e32 v87, v87, v35
	v_sub_f32_e32 v86, v86, v35
	v_sub_f32_e32 v85, v85, v35
	v_sub_f32_e32 v84, v84, v35
	v_sub_f32_e32 v83, v83, v35
	v_sub_f32_e32 v82, v82, v35
	v_sub_f32_e32 v65, v65, v35
	v_sub_f32_e32 v64, v64, v35
	v_sub_f32_e32 v63, v63, v35
	v_sub_f32_e32 v62, v62, v35
	v_sub_f32_e32 v61, v61, v35
	v_sub_f32_e32 v60, v60, v35
	v_sub_f32_e32 v59, v59, v35
	v_sub_f32_e32 v58, v58, v35
	v_sub_f32_e32 v57, v57, v35
	v_sub_f32_e32 v56, v56, v35
	v_sub_f32_e32 v55, v55, v35
	v_sub_f32_e32 v54, v54, v35
	v_sub_f32_e32 v53, v53, v35
	v_sub_f32_e32 v52, v52, v35
	v_sub_f32_e32 v51, v51, v35
	v_sub_f32_e32 v50, v50, v35
	v_mul_f32_e32 v242, v242, v0
	v_mov_b32_e32 v35, v34
	v_mov_b32_e32 v36, v34
	v_mov_b32_e32 v37, v34
	v_mov_b32_e32 v38, v34
	v_mov_b32_e32 v39, v34
	v_mov_b32_e32 v40, v34
	v_mov_b32_e32 v41, v34
	v_mov_b32_e32 v42, v34
	v_mov_b32_e32 v43, v34
	v_mov_b32_e32 v44, v34
	v_mov_b32_e32 v45, v34
	v_mov_b32_e32 v46, v34
	v_mov_b32_e32 v47, v34
	v_mov_b32_e32 v48, v34
	v_mov_b32_e32 v49, v34
	v_mov_b32_e32 v66, v34
	v_mov_b32_e32 v67, v34
	v_mov_b32_e32 v68, v34
	v_mov_b32_e32 v69, v34
	v_mov_b32_e32 v70, v34
	v_mov_b32_e32 v71, v34
	v_mov_b32_e32 v72, v34
	v_mov_b32_e32 v73, v34
	v_mov_b32_e32 v74, v34
	v_mov_b32_e32 v75, v34
	v_mov_b32_e32 v76, v34
	v_mov_b32_e32 v77, v34
	v_mov_b32_e32 v78, v34
	v_mov_b32_e32 v79, v34
	v_mov_b32_e32 v80, v34
	v_mov_b32_e32 v81, v34
	s_branch .LBB0_555
.Lmla_rs1:
	v_frexp_exp_i32_f32_e32 v34, v34
	v_cvt_f32_i32_e32 v34, v34
	v_cndmask_b32_e32 v35, 0, v34, vcc
	v_exp_f32_e64 v36, -v35
	v_add_f32_e32 v235, v235, v35
	v_xor_b32_e32 v34, 0x80000000, v235
	v_sub_f32_e32 v129, v129, v35
	v_pk_mul_f32 v[32:33], v[32:33], v[36:37] op_sel_hi:[1,0]
	v_pk_mul_f32 v[30:31], v[30:31], v[36:37] op_sel_hi:[1,0]
	v_pk_mul_f32 v[28:29], v[28:29], v[36:37] op_sel_hi:[1,0]
	v_pk_mul_f32 v[26:27], v[26:27], v[36:37] op_sel_hi:[1,0]
	v_pk_mul_f32 v[24:25], v[24:25], v[36:37] op_sel_hi:[1,0]
	v_pk_mul_f32 v[22:23], v[22:23], v[36:37] op_sel_hi:[1,0]
	v_pk_mul_f32 v[20:21], v[20:21], v[36:37] op_sel_hi:[1,0]
	v_pk_mul_f32 v[18:19], v[18:19], v[36:37] op_sel_hi:[1,0]
	v_pk_mul_f32 v[16:17], v[16:17], v[36:37] op_sel_hi:[1,0]
	v_pk_mul_f32 v[14:15], v[14:15], v[36:37] op_sel_hi:[1,0]
	v_pk_mul_f32 v[12:13], v[12:13], v[36:37] op_sel_hi:[1,0]
	v_pk_mul_f32 v[10:11], v[10:11], v[36:37] op_sel_hi:[1,0]
	v_pk_mul_f32 v[8:9], v[8:9], v[36:37] op_sel_hi:[1,0]
	v_pk_mul_f32 v[6:7], v[6:7], v[36:37] op_sel_hi:[1,0]
	v_pk_mul_f32 v[4:5], v[4:5], v[36:37] op_sel_hi:[1,0]
	v_pk_mul_f32 v[2:3], v[2:3], v[36:37] op_sel_hi:[1,0]
	v_sub_f32_e32 v128, v128, v35
	v_sub_f32_e32 v127, v127, v35
	v_sub_f32_e32 v126, v126, v35
	v_sub_f32_e32 v125, v125, v35
	v_sub_f32_e32 v124, v124, v35
	v_sub_f32_e32 v123, v123, v35
	v_sub_f32_e32 v122, v122, v35
	v_sub_f32_e32 v121, v121, v35
	v_sub_f32_e32 v120, v120, v35
	v_sub_f32_e32 v119, v119, v35
	v_sub_f32_e32 v118, v118, v35
	v_sub_f32_e32 v117, v117, v35
	v_sub_f32_e32 v116, v116, v35
	v_sub_f32_e32 v115, v115, v35
	v_sub_f32_e32 v114, v114, v35
	v_sub_f32_e32 v113, v113, v35
	v_sub_f32_e32 v112, v112, v35
	v_sub_f32_e32 v111, v111, v35
	v_sub_f32_e32 v110, v110, v35
	v_sub_f32_e32 v109, v109, v35
	v_sub_f32_e32 v108, v108, v35
	v_sub_f32_e32 v107, v107, v35
	v_sub_f32_e32 v106, v106, v35
	v_sub_f32_e32 v105, v105, v35
	v_sub_f32_e32 v104, v104, v35
	v_sub_f32_e32 v103, v103, v35
	v_sub_f32_e32 v102, v102, v35
	v_sub_f32_e32 v101, v101, v35
	v_sub_f32_e32 v100, v100, v35
	v_sub_f32_e32 v99, v99, v35
	v_sub_f32_e32 v98, v98, v35
	v_mul_f32_e32 v0, v0, v36
	v_mov_b32_e32 v35, v34
	v_mov_b32_e32 v36, v34
	v_mov_b32_e32 v37, v34
	v_mov_b32_e32 v38, v34
	v_mov_b32_e32 v39, v34
	v_mov_b32_e32 v40, v34
	v_mov_b32_e32 v41, v34
	v_mov_b32_e32 v42, v34
	v_mov_b32_e32 v43, v34
	v_mov_b32_e32 v44, v34
	v_mov_b32_e32 v45, v34
	v_mov_b32_e32 v46, v34
	v_mov_b32_e32 v47, v34
	v_mov_b32_e32 v48, v34
	v_mov_b32_e32 v49, v34
	v_mov_b32_e32 v66, v34
	v_mov_b32_e32 v67, v34
	v_mov_b32_e32 v68, v34
	v_mov_b32_e32 v69, v34
	v_mov_b32_e32 v70, v34
	v_mov_b32_e32 v71, v34
	v_mov_b32_e32 v72, v34
	v_mov_b32_e32 v73, v34
	v_mov_b32_e32 v74, v34
	v_mov_b32_e32 v75, v34
	v_mov_b32_e32 v76, v34
	v_mov_b32_e32 v77, v34
	v_mov_b32_e32 v78, v34
	v_mov_b32_e32 v79, v34
	v_mov_b32_e32 v80, v34
	v_mov_b32_e32 v81, v34
	s_branch .Lmla_j1
